# also bracket the NSA-window and SWA tile MFMA bursts with s_setprio 1/0
# baseline (speedup 1.0000x reference)
.LBB0_255:
	s_or_b32 s16, s44, s23
	s_cmp_gt_i32 s16, s18
	s_cbranch_scc1 .LBB0_254
	s_lshl_b32 s16, s16, 14
	s_and_b32 s16, s16, 0xc000
	s_add_i32 s16, s16, 0
	s_waitcnt lgkmcnt(0)
	v_add_u32_e32 v50, s16, v215
	v_and_b32_e32 v51, 64, v147
	v_add_u32_e32 v232, v50, v213
	v_add_u32_e32 v82, 64, v51
	v_add_u32_e32 v165, v50, v214
	ds_read_b128 v[70:73], v232 offset:32768
	ds_read_b128 v[74:77], v232 offset:34816
	ds_read_b128 v[78:81], v165 offset:32768
	ds_read_b128 v[66:69], v165 offset:34816
	ds_read_b128 v[62:65], v232 offset:36864
	ds_read_b128 v[54:57], v232 offset:38912
	ds_read_b128 v[58:61], v165 offset:36864
	ds_read_b128 v[50:53], v165 offset:38912
	s_add_i32 s42, s44, s71
	s_lshl_b32 s82, s42, 6
	s_or_b32 s42, s82, 63
	s_cmp_le_u32 s42, s5
	v_xor_b32_e32 v0, 16, v147
	s_cselect_b64 s[42:43], -1, 0
	s_cmp_gt_i32 s82, s19
	v_cmp_lt_i32_e32 vcc, v0, v82
	v_xor_b32_e32 v83, 32, v147
	s_cselect_b64 s[44:45], -1, 0
	v_cndmask_b32_e32 v0, v147, v0, vcc
	v_cmp_lt_i32_e32 vcc, v83, v82
	s_and_b64 s[42:43], s[42:43], s[44:45]
	v_lshlrev_b32_e32 v0, 2, v0
	v_cndmask_b32_e32 v82, v147, v83, vcc
	v_lshlrev_b32_e32 v149, 2, v82
	s_andn2_b64 vcc, exec, s[42:43]
	s_mov_b64 s[42:43], -1
	s_cbranch_vccz .Lsw_p1
	v_lshl_add_u32 v114, s82, 2, v145
	ds_read2_b32 v[82:83], v114 offset0:127 offset1:128
	ds_read2_b32 v[84:85], v114 offset0:129 offset1:130
	ds_read2_b32 v[86:87], v114 offset0:143 offset1:144
	ds_read2_b32 v[88:89], v114 offset0:145 offset1:146
	s_waitcnt lgkmcnt(4)
	s_setprio 1
	v_mfma_f32_16x16x32_bf16 v[70:73], v[70:73], v[2:5], 0
	v_mfma_f32_16x16x32_bf16 v[74:77], v[74:77], v[2:5], 0
	v_mfma_f32_16x16x32_bf16 v[62:65], v[62:65], v[2:5], 0
	v_mfma_f32_16x16x32_bf16 v[54:57], v[54:57], v[2:5], 0
	ds_read2_b32 v[90:91], v114 offset0:159 offset1:160
	ds_read2_b32 v[92:93], v114 offset0:161 offset1:162
	ds_read2_b32 v[94:95], v114 offset0:175 offset1:176
	ds_read2_b32 v[96:97], v114 offset0:177 offset1:178
	v_mfma_f32_16x16x32_bf16 v[70:73], v[78:81], v[6:9], v[70:73]
	v_mfma_f32_16x16x32_bf16 v[74:77], v[66:69], v[6:9], v[74:77]
	v_mfma_f32_16x16x32_bf16 v[62:65], v[58:61], v[6:9], v[62:65]
	v_mfma_f32_16x16x32_bf16 v[54:57], v[50:53], v[6:9], v[54:57]
	s_setprio 0
	s_waitcnt lgkmcnt(0)
	ds_read_b128 v[98:101], v232 offset:32768
	ds_read_b128 v[78:81], v165 offset:32768
	ds_read_b128 v[102:105], v232 offset:34816
	ds_read_b128 v[66:69], v165 offset:34816
	ds_read_b128 v[106:109], v232 offset:36864
	ds_read_b128 v[58:61], v165 offset:36864
	ds_read_b128 v[110:113], v232 offset:38912
	ds_read_b128 v[50:53], v165 offset:38912
	v_pk_fma_f32 v[70:71], v[70:71], s[36:37], v[82:83] op_sel_hi:[1,0,1]
	v_pk_fma_f32 v[72:73], v[72:73], s[36:37], v[84:85] op_sel_hi:[1,0,1]
	v_pk_fma_f32 v[74:75], v[74:75], s[36:37], v[86:87] op_sel_hi:[1,0,1]
	v_pk_fma_f32 v[76:77], v[76:77], s[36:37], v[88:89] op_sel_hi:[1,0,1]
	v_pk_fma_f32 v[62:63], v[62:63], s[36:37], v[90:91] op_sel_hi:[1,0,1]
	v_pk_fma_f32 v[64:65], v[64:65], s[36:37], v[92:93] op_sel_hi:[1,0,1]
	v_pk_fma_f32 v[54:55], v[54:55], s[36:37], v[94:95] op_sel_hi:[1,0,1]
	v_pk_fma_f32 v[56:57], v[56:57], s[36:37], v[96:97] op_sel_hi:[1,0,1]
	v_or_b32_e32 v117, s82, v216
	v_sub_u32_e32 v115, v144, v117
	v_subrev_u32_e32 v117, 0, v115
	v_cmp_gt_u32_e64 s[48:49], s26, v117
	v_subrev_u32_e32 v117, 1, v115
	v_cmp_gt_u32_e64 s[50:51], s26, v117
	v_subrev_u32_e32 v117, 2, v115
	v_cmp_gt_u32_e64 s[52:53], s26, v117
	v_subrev_u32_e32 v117, 3, v115
	v_cmp_gt_u32_e64 s[54:55], s26, v117
	v_subrev_u32_e32 v117, 16, v115
	v_cmp_gt_u32_e64 s[56:57], s26, v117
	v_subrev_u32_e32 v117, 17, v115
	v_cmp_gt_u32_e64 s[58:59], s26, v117
	v_subrev_u32_e32 v117, 18, v115
	v_cmp_gt_u32_e64 s[60:61], s26, v117
	v_subrev_u32_e32 v117, 19, v115
	v_cmp_gt_u32_e64 s[62:63], s26, v117
	v_cndmask_b32_e64 v70, v148, v70, s[48:49]
	v_cndmask_b32_e64 v71, v148, v71, s[50:51]
	v_cndmask_b32_e64 v72, v148, v72, s[52:53]
	v_cndmask_b32_e64 v73, v148, v73, s[54:55]
	v_cndmask_b32_e64 v74, v148, v74, s[56:57]
	v_cndmask_b32_e64 v75, v148, v75, s[58:59]
	v_cndmask_b32_e64 v76, v148, v76, s[60:61]
	v_cndmask_b32_e64 v77, v148, v77, s[62:63]
	v_subrev_u32_e32 v117, 32, v115
	v_cmp_gt_u32_e64 s[48:49], s26, v117
	v_subrev_u32_e32 v117, 33, v115
	v_cmp_gt_u32_e64 s[50:51], s26, v117
	v_subrev_u32_e32 v117, 34, v115
	v_cmp_gt_u32_e64 s[52:53], s26, v117
	v_subrev_u32_e32 v117, 35, v115
	v_cmp_gt_u32_e64 s[54:55], s26, v117
	v_subrev_u32_e32 v117, 48, v115
	v_cmp_gt_u32_e64 s[56:57], s26, v117
	v_subrev_u32_e32 v117, 49, v115
	v_cmp_gt_u32_e64 s[58:59], s26, v117
	v_subrev_u32_e32 v117, 50, v115
	v_cmp_gt_u32_e64 s[60:61], s26, v117
	v_subrev_u32_e32 v117, 51, v115
	v_cmp_gt_u32_e64 s[62:63], s26, v117
	v_cndmask_b32_e64 v62, v148, v62, s[48:49]
	v_cndmask_b32_e64 v63, v148, v63, s[50:51]
	v_cndmask_b32_e64 v64, v148, v64, s[52:53]
	v_cndmask_b32_e64 v65, v148, v65, s[54:55]
	v_cndmask_b32_e64 v54, v148, v54, s[56:57]
	v_cndmask_b32_e64 v55, v148, v55, s[58:59]
	v_cndmask_b32_e64 v56, v148, v56, s[60:61]
	v_cndmask_b32_e64 v57, v148, v57, s[62:63]
	v_max3_f32 v116, v70, v71, v72
	v_max3_f32 v116, v116, v73, v74
	v_max3_f32 v116, v116, v75, v76
	v_max3_f32 v116, v116, v77, v62
	v_max3_f32 v116, v116, v63, v64
	v_max3_f32 v116, v116, v65, v54
	v_max3_f32 v116, v116, v55, v56
	v_max3_f32 v116, v116, v57, s29
	v_mov_b32_e32 v117, v116
	s_nop 1
	v_permlane16_swap_b32_e32 v116, v117
	v_max_f32_e32 v116, v116, v117
	v_mov_b32_e32 v117, v116
	s_nop 1
	v_permlane32_swap_b32_e32 v116, v117
	v_max_f32_e32 v116, v116, v117
	v_max_f32_e32 v121, v166, v116
	v_sub_f32_e32 v118, v166, v121
	v_cmp_lt_f32_e32 vcc, s30, v121
	v_exp_f32_e32 v118, v118
	v_mov_b32_e32 v166, v121
	v_cndmask_b32_e32 v120, 0, v121, vcc
	v_pk_mul_f32 v[46:47], v[46:47], v[118:119] op_sel_hi:[1,0]
	v_pk_mul_f32 v[48:49], v[48:49], v[118:119] op_sel_hi:[1,0]
	v_pk_mul_f32 v[42:43], v[42:43], v[118:119] op_sel_hi:[1,0]
	v_pk_mul_f32 v[44:45], v[44:45], v[118:119] op_sel_hi:[1,0]
	v_pk_mul_f32 v[38:39], v[38:39], v[118:119] op_sel_hi:[1,0]
	v_pk_mul_f32 v[40:41], v[40:41], v[118:119] op_sel_hi:[1,0]
	v_pk_mul_f32 v[34:35], v[34:35], v[118:119] op_sel_hi:[1,0]
	v_pk_mul_f32 v[36:37], v[36:37], v[118:119] op_sel_hi:[1,0]
	v_pk_add_f32 v[70:71], v[70:71], v[120:121] op_sel_hi:[1,0] neg_lo:[0,1] neg_hi:[0,1]
	v_pk_add_f32 v[72:73], v[72:73], v[120:121] op_sel_hi:[1,0] neg_lo:[0,1] neg_hi:[0,1]
	v_pk_add_f32 v[74:75], v[74:75], v[120:121] op_sel_hi:[1,0] neg_lo:[0,1] neg_hi:[0,1]
	v_pk_add_f32 v[76:77], v[76:77], v[120:121] op_sel_hi:[1,0] neg_lo:[0,1] neg_hi:[0,1]
	v_pk_add_f32 v[62:63], v[62:63], v[120:121] op_sel_hi:[1,0] neg_lo:[0,1] neg_hi:[0,1]
	v_pk_add_f32 v[64:65], v[64:65], v[120:121] op_sel_hi:[1,0] neg_lo:[0,1] neg_hi:[0,1]
	v_pk_add_f32 v[54:55], v[54:55], v[120:121] op_sel_hi:[1,0] neg_lo:[0,1] neg_hi:[0,1]
	v_pk_add_f32 v[56:57], v[56:57], v[120:121] op_sel_hi:[1,0] neg_lo:[0,1] neg_hi:[0,1]
	v_exp_f32_e32 v70, v70
	v_exp_f32_e32 v71, v71
	v_exp_f32_e32 v72, v72
	v_exp_f32_e32 v73, v73
	v_exp_f32_e32 v74, v74
	v_exp_f32_e32 v75, v75
	v_exp_f32_e32 v76, v76
	v_exp_f32_e32 v77, v77
	v_exp_f32_e32 v62, v62
	v_exp_f32_e32 v63, v63
	v_exp_f32_e32 v64, v64
	v_exp_f32_e32 v65, v65
	v_exp_f32_e32 v54, v54
	v_exp_f32_e32 v55, v55
	v_exp_f32_e32 v56, v56
	v_exp_f32_e32 v57, v57
	s_nop 0
	v_pk_add_f32 v[82:83], v[70:71], v[72:73]
	v_pk_add_f32 v[84:85], v[74:75], v[76:77]
	v_pk_add_f32 v[86:87], v[62:63], v[64:65]
	v_pk_add_f32 v[88:89], v[54:55], v[56:57]
	v_pk_add_f32 v[82:83], v[82:83], v[84:85]
	v_pk_add_f32 v[86:87], v[86:87], v[88:89]
	s_nop 0
	v_pk_add_f32 v[82:83], v[82:83], v[86:87]
	s_nop 0
	v_add_f32_e32 v82, v82, v83
	v_fma_f32 v158, v158, v118, v82
	v_cvt_pk_bf16_f32 v77, v76, v77
	v_cvt_pk_bf16_f32 v76, v74, v75
	v_cvt_pk_bf16_f32 v75, v72, v73
	v_cvt_pk_bf16_f32 v74, v70, v71
	v_cvt_pk_bf16_f32 v62, v62, v63
	v_cvt_pk_bf16_f32 v63, v64, v65
	v_cvt_pk_bf16_f32 v64, v54, v55
	v_cvt_pk_bf16_f32 v65, v56, v57
	s_waitcnt lgkmcnt(0)
	ds_read2_b32 v[82:83], v114 offset0:111 offset1:112
	ds_read2_b32 v[84:85], v114 offset0:113 offset1:114
	ds_read2_b32 v[86:87], v114 offset0:127 offset1:128
	ds_read2_b32 v[88:89], v114 offset0:129 offset1:130
	ds_read2_b32 v[90:91], v114 offset0:143 offset1:144
	ds_read2_b32 v[92:93], v114 offset0:145 offset1:146
	ds_read2_b32 v[94:95], v114 offset0:159 offset1:160
	ds_read2_b32 v[96:97], v114 offset0:161 offset1:162
	s_setprio 1
	v_mfma_f32_16x16x32_bf16 v[98:101], v[98:101], v[10:13], 0
	v_mfma_f32_16x16x32_bf16 v[102:105], v[102:105], v[10:13], 0
	v_mfma_f32_16x16x32_bf16 v[106:109], v[106:109], v[10:13], 0
	v_mfma_f32_16x16x32_bf16 v[110:113], v[110:113], v[10:13], 0
	v_mfma_f32_16x16x32_bf16 v[98:101], v[78:81], v[14:17], v[98:101]
	v_mfma_f32_16x16x32_bf16 v[102:105], v[66:69], v[14:17], v[102:105]
	v_mfma_f32_16x16x32_bf16 v[106:109], v[58:61], v[14:17], v[106:109]
	v_mfma_f32_16x16x32_bf16 v[110:113], v[50:53], v[14:17], v[110:113]
	s_setprio 0
	s_waitcnt lgkmcnt(0)
	s_nop 6
	v_pk_fma_f32 v[98:99], v[98:99], s[36:37], v[82:83] op_sel_hi:[1,0,1]
	v_pk_fma_f32 v[100:101], v[100:101], s[36:37], v[84:85] op_sel_hi:[1,0,1]
	v_pk_fma_f32 v[102:103], v[102:103], s[36:37], v[86:87] op_sel_hi:[1,0,1]
	v_pk_fma_f32 v[104:105], v[104:105], s[36:37], v[88:89] op_sel_hi:[1,0,1]
	v_pk_fma_f32 v[106:107], v[106:107], s[36:37], v[90:91] op_sel_hi:[1,0,1]
	v_pk_fma_f32 v[108:109], v[108:109], s[36:37], v[92:93] op_sel_hi:[1,0,1]
	v_pk_fma_f32 v[110:111], v[110:111], s[36:37], v[94:95] op_sel_hi:[1,0,1]
	v_pk_fma_f32 v[112:113], v[112:113], s[36:37], v[96:97] op_sel_hi:[1,0,1]
	v_or_b32_e32 v117, s82, v216
	v_sub_u32_e32 v115, v144, v117
	v_add_u32_e32 v115, 16, v115
	v_subrev_u32_e32 v117, 0, v115
	v_cmp_gt_u32_e64 s[48:49], s26, v117
	v_subrev_u32_e32 v117, 1, v115
	v_cmp_gt_u32_e64 s[50:51], s26, v117
	v_subrev_u32_e32 v117, 2, v115
	v_cmp_gt_u32_e64 s[52:53], s26, v117
	v_subrev_u32_e32 v117, 3, v115
	v_cmp_gt_u32_e64 s[54:55], s26, v117
	v_subrev_u32_e32 v117, 16, v115
	v_cmp_gt_u32_e64 s[56:57], s26, v117
	v_subrev_u32_e32 v117, 17, v115
	v_cmp_gt_u32_e64 s[58:59], s26, v117
	v_subrev_u32_e32 v117, 18, v115
	v_cmp_gt_u32_e64 s[60:61], s26, v117
	v_subrev_u32_e32 v117, 19, v115
	v_cmp_gt_u32_e64 s[62:63], s26, v117
	v_cndmask_b32_e64 v98, v148, v98, s[48:49]
	v_cndmask_b32_e64 v99, v148, v99, s[50:51]
	v_cndmask_b32_e64 v100, v148, v100, s[52:53]
	v_cndmask_b32_e64 v101, v148, v101, s[54:55]
	v_cndmask_b32_e64 v102, v148, v102, s[56:57]
	v_cndmask_b32_e64 v103, v148, v103, s[58:59]
	v_cndmask_b32_e64 v104, v148, v104, s[60:61]
	v_cndmask_b32_e64 v105, v148, v105, s[62:63]
	v_subrev_u32_e32 v117, 32, v115
	v_cmp_gt_u32_e64 s[48:49], s26, v117
	v_subrev_u32_e32 v117, 33, v115
	v_cmp_gt_u32_e64 s[50:51], s26, v117
	v_subrev_u32_e32 v117, 34, v115
	v_cmp_gt_u32_e64 s[52:53], s26, v117
	v_subrev_u32_e32 v117, 35, v115
	v_cmp_gt_u32_e64 s[54:55], s26, v117
	v_subrev_u32_e32 v117, 48, v115
	v_cmp_gt_u32_e64 s[56:57], s26, v117
	v_subrev_u32_e32 v117, 49, v115
	v_cmp_gt_u32_e64 s[58:59], s26, v117
	v_subrev_u32_e32 v117, 50, v115
	v_cmp_gt_u32_e64 s[60:61], s26, v117
	v_subrev_u32_e32 v117, 51, v115
	v_cmp_gt_u32_e64 s[62:63], s26, v117
	v_cndmask_b32_e64 v106, v148, v106, s[48:49]
	v_cndmask_b32_e64 v107, v148, v107, s[50:51]
	v_cndmask_b32_e64 v108, v148, v108, s[52:53]
	v_cndmask_b32_e64 v109, v148, v109, s[54:55]
	v_cndmask_b32_e64 v110, v148, v110, s[56:57]
	v_cndmask_b32_e64 v111, v148, v111, s[58:59]
	v_cndmask_b32_e64 v112, v148, v112, s[60:61]
	v_cndmask_b32_e64 v113, v148, v113, s[62:63]
	v_max3_f32 v116, v98, v99, v100
	v_max3_f32 v116, v116, v101, v102
	v_max3_f32 v116, v116, v103, v104
	v_max3_f32 v116, v116, v105, v106
	v_max3_f32 v116, v116, v107, v108
	v_max3_f32 v116, v116, v109, v110
	v_max3_f32 v116, v116, v111, v112
	v_max3_f32 v116, v116, v113, s29
	v_mov_b32_e32 v117, v116
	s_nop 1
	v_permlane16_swap_b32_e32 v116, v117
	v_max_f32_e32 v116, v116, v117
	v_mov_b32_e32 v117, v116
	s_nop 1
	v_permlane32_swap_b32_e32 v116, v117
	v_max_f32_e32 v116, v116, v117
	v_max_f32_e32 v121, v167, v116
	v_sub_f32_e32 v118, v167, v121
	v_cmp_lt_f32_e32 vcc, s30, v121
	v_exp_f32_e32 v118, v118
	v_mov_b32_e32 v167, v121
	v_cndmask_b32_e32 v120, 0, v121, vcc
	v_pk_mul_f32 v[30:31], v[30:31], v[118:119] op_sel_hi:[1,0]
	v_pk_mul_f32 v[32:33], v[32:33], v[118:119] op_sel_hi:[1,0]
	v_pk_mul_f32 v[26:27], v[26:27], v[118:119] op_sel_hi:[1,0]
	v_pk_mul_f32 v[28:29], v[28:29], v[118:119] op_sel_hi:[1,0]
	v_pk_mul_f32 v[22:23], v[22:23], v[118:119] op_sel_hi:[1,0]
	v_pk_mul_f32 v[24:25], v[24:25], v[118:119] op_sel_hi:[1,0]
	v_pk_mul_f32 v[18:19], v[18:19], v[118:119] op_sel_hi:[1,0]
	v_pk_mul_f32 v[20:21], v[20:21], v[118:119] op_sel_hi:[1,0]
	v_pk_add_f32 v[98:99], v[98:99], v[120:121] op_sel_hi:[1,0] neg_lo:[0,1] neg_hi:[0,1]
	v_pk_add_f32 v[100:101], v[100:101], v[120:121] op_sel_hi:[1,0] neg_lo:[0,1] neg_hi:[0,1]
	v_pk_add_f32 v[102:103], v[102:103], v[120:121] op_sel_hi:[1,0] neg_lo:[0,1] neg_hi:[0,1]
	v_pk_add_f32 v[104:105], v[104:105], v[120:121] op_sel_hi:[1,0] neg_lo:[0,1] neg_hi:[0,1]
	v_pk_add_f32 v[106:107], v[106:107], v[120:121] op_sel_hi:[1,0] neg_lo:[0,1] neg_hi:[0,1]
	v_pk_add_f32 v[108:109], v[108:109], v[120:121] op_sel_hi:[1,0] neg_lo:[0,1] neg_hi:[0,1]
	v_pk_add_f32 v[110:111], v[110:111], v[120:121] op_sel_hi:[1,0] neg_lo:[0,1] neg_hi:[0,1]
	v_pk_add_f32 v[112:113], v[112:113], v[120:121] op_sel_hi:[1,0] neg_lo:[0,1] neg_hi:[0,1]
	v_exp_f32_e32 v98, v98
	v_exp_f32_e32 v99, v99
	v_exp_f32_e32 v100, v100
	v_exp_f32_e32 v101, v101
	v_exp_f32_e32 v102, v102
	v_exp_f32_e32 v103, v103
	v_exp_f32_e32 v104, v104
	v_exp_f32_e32 v105, v105
	v_exp_f32_e32 v106, v106
	v_exp_f32_e32 v107, v107
	v_exp_f32_e32 v108, v108
	v_exp_f32_e32 v109, v109
	v_exp_f32_e32 v110, v110
	v_exp_f32_e32 v111, v111
	v_exp_f32_e32 v112, v112
	v_exp_f32_e32 v113, v113
	s_nop 0
	v_pk_add_f32 v[82:83], v[98:99], v[100:101]
	v_pk_add_f32 v[84:85], v[102:103], v[104:105]
	v_pk_add_f32 v[86:87], v[106:107], v[108:109]
	v_pk_add_f32 v[88:89], v[110:111], v[112:113]
	v_pk_add_f32 v[82:83], v[82:83], v[84:85]
	v_pk_add_f32 v[86:87], v[86:87], v[88:89]
	s_nop 0
	v_pk_add_f32 v[82:83], v[82:83], v[86:87]
	s_nop 0
	v_add_f32_e32 v82, v82, v83
	v_fma_f32 v159, v159, v118, v82
	v_cvt_pk_bf16_f32 v105, v104, v105
	v_cvt_pk_bf16_f32 v104, v102, v103
	v_cvt_pk_bf16_f32 v103, v100, v101
	v_cvt_pk_bf16_f32 v102, v98, v99
	v_cvt_pk_bf16_f32 v106, v106, v107
	v_cvt_pk_bf16_f32 v107, v108, v109
	v_cvt_pk_bf16_f32 v108, v110, v111
	v_cvt_pk_bf16_f32 v109, v112, v113
	s_branch .Lsw_pv
.Lsw_p1:
	v_lshl_add_u32 v114, s82, 2, v145
	ds_read2_b32 v[82:83], v114 offset0:127 offset1:128
	ds_read2_b32 v[84:85], v114 offset0:129 offset1:130
	ds_read2_b32 v[86:87], v114 offset0:143 offset1:144
	ds_read2_b32 v[88:89], v114 offset0:145 offset1:146
	s_waitcnt lgkmcnt(4)
	s_setprio 1
	v_mfma_f32_16x16x32_bf16 v[70:73], v[70:73], v[2:5], 0
	v_mfma_f32_16x16x32_bf16 v[74:77], v[74:77], v[2:5], 0
	v_mfma_f32_16x16x32_bf16 v[62:65], v[62:65], v[2:5], 0
	v_mfma_f32_16x16x32_bf16 v[54:57], v[54:57], v[2:5], 0
	ds_read2_b32 v[90:91], v114 offset0:159 offset1:160
	ds_read2_b32 v[92:93], v114 offset0:161 offset1:162
	ds_read2_b32 v[94:95], v114 offset0:175 offset1:176
	ds_read2_b32 v[96:97], v114 offset0:177 offset1:178
	v_mfma_f32_16x16x32_bf16 v[70:73], v[78:81], v[6:9], v[70:73]
	v_mfma_f32_16x16x32_bf16 v[74:77], v[66:69], v[6:9], v[74:77]
	v_mfma_f32_16x16x32_bf16 v[62:65], v[58:61], v[6:9], v[62:65]
	v_mfma_f32_16x16x32_bf16 v[54:57], v[50:53], v[6:9], v[54:57]
	s_setprio 0
	s_waitcnt lgkmcnt(0)
	ds_read_b128 v[98:101], v232 offset:32768
	ds_read_b128 v[78:81], v165 offset:32768
	ds_read_b128 v[102:105], v232 offset:34816
	ds_read_b128 v[66:69], v165 offset:34816
	ds_read_b128 v[106:109], v232 offset:36864
	ds_read_b128 v[58:61], v165 offset:36864
	ds_read_b128 v[110:113], v232 offset:38912
	ds_read_b128 v[50:53], v165 offset:38912
	v_pk_fma_f32 v[70:71], v[70:71], s[36:37], v[82:83] op_sel_hi:[1,0,1]
	v_pk_fma_f32 v[72:73], v[72:73], s[36:37], v[84:85] op_sel_hi:[1,0,1]
	v_pk_fma_f32 v[74:75], v[74:75], s[36:37], v[86:87] op_sel_hi:[1,0,1]
	v_pk_fma_f32 v[76:77], v[76:77], s[36:37], v[88:89] op_sel_hi:[1,0,1]
	v_pk_fma_f32 v[62:63], v[62:63], s[36:37], v[90:91] op_sel_hi:[1,0,1]
	v_pk_fma_f32 v[64:65], v[64:65], s[36:37], v[92:93] op_sel_hi:[1,0,1]
	v_pk_fma_f32 v[54:55], v[54:55], s[36:37], v[94:95] op_sel_hi:[1,0,1]
	v_pk_fma_f32 v[56:57], v[56:57], s[36:37], v[96:97] op_sel_hi:[1,0,1]
	v_max3_f32 v116, v70, v71, v72
	v_max3_f32 v116, v116, v73, v74
	v_max3_f32 v116, v116, v75, v76
	v_max3_f32 v116, v116, v77, v62
	v_max3_f32 v116, v116, v63, v64
	v_max3_f32 v116, v116, v65, v54
	v_max3_f32 v116, v116, v55, v56
	v_max3_f32 v116, v116, v57, s29
	v_mov_b32_e32 v117, v116
	s_nop 1
	v_permlane16_swap_b32_e32 v116, v117
	v_max_f32_e32 v116, v116, v117
	v_mov_b32_e32 v117, v116
	s_nop 1
	v_permlane32_swap_b32_e32 v116, v117
	v_max_f32_e32 v116, v116, v117
	v_max_f32_e32 v121, v166, v116
	v_sub_f32_e32 v118, v166, v121
	v_exp_f32_e32 v118, v118
	v_mov_b32_e32 v166, v121
	v_mov_b32_e32 v120, v121
	v_pk_mul_f32 v[46:47], v[46:47], v[118:119] op_sel_hi:[1,0]
	v_pk_mul_f32 v[48:49], v[48:49], v[118:119] op_sel_hi:[1,0]
	v_pk_mul_f32 v[42:43], v[42:43], v[118:119] op_sel_hi:[1,0]
	v_pk_mul_f32 v[44:45], v[44:45], v[118:119] op_sel_hi:[1,0]
	v_pk_mul_f32 v[38:39], v[38:39], v[118:119] op_sel_hi:[1,0]
	v_pk_mul_f32 v[40:41], v[40:41], v[118:119] op_sel_hi:[1,0]
	v_pk_mul_f32 v[34:35], v[34:35], v[118:119] op_sel_hi:[1,0]
	v_pk_mul_f32 v[36:37], v[36:37], v[118:119] op_sel_hi:[1,0]
	v_pk_add_f32 v[70:71], v[70:71], v[120:121] op_sel_hi:[1,0] neg_lo:[0,1] neg_hi:[0,1]
	v_pk_add_f32 v[72:73], v[72:73], v[120:121] op_sel_hi:[1,0] neg_lo:[0,1] neg_hi:[0,1]
	v_pk_add_f32 v[74:75], v[74:75], v[120:121] op_sel_hi:[1,0] neg_lo:[0,1] neg_hi:[0,1]
	v_pk_add_f32 v[76:77], v[76:77], v[120:121] op_sel_hi:[1,0] neg_lo:[0,1] neg_hi:[0,1]
	v_pk_add_f32 v[62:63], v[62:63], v[120:121] op_sel_hi:[1,0] neg_lo:[0,1] neg_hi:[0,1]
	v_pk_add_f32 v[64:65], v[64:65], v[120:121] op_sel_hi:[1,0] neg_lo:[0,1] neg_hi:[0,1]
	v_pk_add_f32 v[54:55], v[54:55], v[120:121] op_sel_hi:[1,0] neg_lo:[0,1] neg_hi:[0,1]
	v_pk_add_f32 v[56:57], v[56:57], v[120:121] op_sel_hi:[1,0] neg_lo:[0,1] neg_hi:[0,1]
	v_exp_f32_e32 v70, v70
	v_exp_f32_e32 v71, v71
	v_exp_f32_e32 v72, v72
	v_exp_f32_e32 v73, v73
	v_exp_f32_e32 v74, v74
	v_exp_f32_e32 v75, v75
	v_exp_f32_e32 v76, v76
	v_exp_f32_e32 v77, v77
	v_exp_f32_e32 v62, v62
	v_exp_f32_e32 v63, v63
	v_exp_f32_e32 v64, v64
	v_exp_f32_e32 v65, v65
	v_exp_f32_e32 v54, v54
	v_exp_f32_e32 v55, v55
	v_exp_f32_e32 v56, v56
	v_exp_f32_e32 v57, v57
	s_nop 0
	v_pk_add_f32 v[82:83], v[70:71], v[72:73]
	v_pk_add_f32 v[84:85], v[74:75], v[76:77]
	v_pk_add_f32 v[86:87], v[62:63], v[64:65]
	v_pk_add_f32 v[88:89], v[54:55], v[56:57]
	v_pk_add_f32 v[82:83], v[82:83], v[84:85]
	v_pk_add_f32 v[86:87], v[86:87], v[88:89]
	s_nop 0
	v_pk_add_f32 v[82:83], v[82:83], v[86:87]
	s_nop 0
	v_add_f32_e32 v82, v82, v83
	v_fma_f32 v158, v158, v118, v82
	v_cvt_pk_bf16_f32 v77, v76, v77
	v_cvt_pk_bf16_f32 v76, v74, v75
	v_cvt_pk_bf16_f32 v75, v72, v73
	v_cvt_pk_bf16_f32 v74, v70, v71
	v_cvt_pk_bf16_f32 v62, v62, v63
	v_cvt_pk_bf16_f32 v63, v64, v65
	v_cvt_pk_bf16_f32 v64, v54, v55
	v_cvt_pk_bf16_f32 v65, v56, v57
	s_waitcnt lgkmcnt(0)
	ds_read2_b32 v[82:83], v114 offset0:111 offset1:112
	ds_read2_b32 v[84:85], v114 offset0:113 offset1:114
	ds_read2_b32 v[86:87], v114 offset0:127 offset1:128
	ds_read2_b32 v[88:89], v114 offset0:129 offset1:130
	ds_read2_b32 v[90:91], v114 offset0:143 offset1:144
	ds_read2_b32 v[92:93], v114 offset0:145 offset1:146
	ds_read2_b32 v[94:95], v114 offset0:159 offset1:160
	ds_read2_b32 v[96:97], v114 offset0:161 offset1:162
	s_setprio 1
	v_mfma_f32_16x16x32_bf16 v[98:101], v[98:101], v[10:13], 0
	v_mfma_f32_16x16x32_bf16 v[102:105], v[102:105], v[10:13], 0
	v_mfma_f32_16x16x32_bf16 v[106:109], v[106:109], v[10:13], 0
	v_mfma_f32_16x16x32_bf16 v[110:113], v[110:113], v[10:13], 0
	v_mfma_f32_16x16x32_bf16 v[98:101], v[78:81], v[14:17], v[98:101]
	v_mfma_f32_16x16x32_bf16 v[102:105], v[66:69], v[14:17], v[102:105]
	v_mfma_f32_16x16x32_bf16 v[106:109], v[58:61], v[14:17], v[106:109]
	v_mfma_f32_16x16x32_bf16 v[110:113], v[50:53], v[14:17], v[110:113]
	s_setprio 0
	s_waitcnt lgkmcnt(0)
	s_nop 6
	v_pk_fma_f32 v[98:99], v[98:99], s[36:37], v[82:83] op_sel_hi:[1,0,1]
	v_pk_fma_f32 v[100:101], v[100:101], s[36:37], v[84:85] op_sel_hi:[1,0,1]
	v_pk_fma_f32 v[102:103], v[102:103], s[36:37], v[86:87] op_sel_hi:[1,0,1]
	v_pk_fma_f32 v[104:105], v[104:105], s[36:37], v[88:89] op_sel_hi:[1,0,1]
	v_pk_fma_f32 v[106:107], v[106:107], s[36:37], v[90:91] op_sel_hi:[1,0,1]
	v_pk_fma_f32 v[108:109], v[108:109], s[36:37], v[92:93] op_sel_hi:[1,0,1]
	v_pk_fma_f32 v[110:111], v[110:111], s[36:37], v[94:95] op_sel_hi:[1,0,1]
	v_pk_fma_f32 v[112:113], v[112:113], s[36:37], v[96:97] op_sel_hi:[1,0,1]
	v_max3_f32 v116, v98, v99, v100
	v_max3_f32 v116, v116, v101, v102
	v_max3_f32 v116, v116, v103, v104
	v_max3_f32 v116, v116, v105, v106
	v_max3_f32 v116, v116, v107, v108
	v_max3_f32 v116, v116, v109, v110
	v_max3_f32 v116, v116, v111, v112
	v_max3_f32 v116, v116, v113, s29
	v_mov_b32_e32 v117, v116
	s_nop 1
	v_permlane16_swap_b32_e32 v116, v117
	v_max_f32_e32 v116, v116, v117
	v_mov_b32_e32 v117, v116
	s_nop 1
	v_permlane32_swap_b32_e32 v116, v117
	v_max_f32_e32 v116, v116, v117
	v_max_f32_e32 v121, v167, v116
	v_sub_f32_e32 v118, v167, v121
	v_exp_f32_e32 v118, v118
	v_mov_b32_e32 v167, v121
	v_mov_b32_e32 v120, v121
	v_pk_mul_f32 v[30:31], v[30:31], v[118:119] op_sel_hi:[1,0]
	v_pk_mul_f32 v[32:33], v[32:33], v[118:119] op_sel_hi:[1,0]
	v_pk_mul_f32 v[26:27], v[26:27], v[118:119] op_sel_hi:[1,0]
	v_pk_mul_f32 v[28:29], v[28:29], v[118:119] op_sel_hi:[1,0]
	v_pk_mul_f32 v[22:23], v[22:23], v[118:119] op_sel_hi:[1,0]
	v_pk_mul_f32 v[24:25], v[24:25], v[118:119] op_sel_hi:[1,0]
	v_pk_mul_f32 v[18:19], v[18:19], v[118:119] op_sel_hi:[1,0]
	v_pk_mul_f32 v[20:21], v[20:21], v[118:119] op_sel_hi:[1,0]
	v_pk_add_f32 v[98:99], v[98:99], v[120:121] op_sel_hi:[1,0] neg_lo:[0,1] neg_hi:[0,1]
	v_pk_add_f32 v[100:101], v[100:101], v[120:121] op_sel_hi:[1,0] neg_lo:[0,1] neg_hi:[0,1]
	v_pk_add_f32 v[102:103], v[102:103], v[120:121] op_sel_hi:[1,0] neg_lo:[0,1] neg_hi:[0,1]
	v_pk_add_f32 v[104:105], v[104:105], v[120:121] op_sel_hi:[1,0] neg_lo:[0,1] neg_hi:[0,1]
	v_pk_add_f32 v[106:107], v[106:107], v[120:121] op_sel_hi:[1,0] neg_lo:[0,1] neg_hi:[0,1]
	v_pk_add_f32 v[108:109], v[108:109], v[120:121] op_sel_hi:[1,0] neg_lo:[0,1] neg_hi:[0,1]
	v_pk_add_f32 v[110:111], v[110:111], v[120:121] op_sel_hi:[1,0] neg_lo:[0,1] neg_hi:[0,1]
	v_pk_add_f32 v[112:113], v[112:113], v[120:121] op_sel_hi:[1,0] neg_lo:[0,1] neg_hi:[0,1]
	v_exp_f32_e32 v98, v98
	v_exp_f32_e32 v99, v99
	v_exp_f32_e32 v100, v100
	v_exp_f32_e32 v101, v101
	v_exp_f32_e32 v102, v102
	v_exp_f32_e32 v103, v103
	v_exp_f32_e32 v104, v104
	v_exp_f32_e32 v105, v105
	v_exp_f32_e32 v106, v106
	v_exp_f32_e32 v107, v107
	v_exp_f32_e32 v108, v108
	v_exp_f32_e32 v109, v109
	v_exp_f32_e32 v110, v110
	v_exp_f32_e32 v111, v111
	v_exp_f32_e32 v112, v112
	v_exp_f32_e32 v113, v113
	s_nop 0
	v_pk_add_f32 v[82:83], v[98:99], v[100:101]
	v_pk_add_f32 v[84:85], v[102:103], v[104:105]
	v_pk_add_f32 v[86:87], v[106:107], v[108:109]
	v_pk_add_f32 v[88:89], v[110:111], v[112:113]
	v_pk_add_f32 v[82:83], v[82:83], v[84:85]
	v_pk_add_f32 v[86:87], v[86:87], v[88:89]
	s_nop 0
	v_pk_add_f32 v[82:83], v[82:83], v[86:87]
	s_nop 0
	v_add_f32_e32 v82, v82, v83
	v_fma_f32 v159, v159, v118, v82
	v_cvt_pk_bf16_f32 v105, v104, v105
	v_cvt_pk_bf16_f32 v104, v102, v103
	v_cvt_pk_bf16_f32 v103, v100, v101
	v_cvt_pk_bf16_f32 v102, v98, v99
	v_cvt_pk_bf16_f32 v106, v106, v107
	v_cvt_pk_bf16_f32 v107, v108, v109
	v_cvt_pk_bf16_f32 v108, v110, v111
	v_cvt_pk_bf16_f32 v109, v112, v113
.Lsw_pv:
	v_add3_u32 v114, s16, v217, v219
	v_add_u32_e32 v115, v114, v220
	v_add_u32_e32 v116, v114, v221
	v_add_u32_e32 v117, v114, v222
	v_add_u32_e32 v119, v114, v223
	ds_read_b64_tr_b16 v[82:83], v115 offset:40960
	ds_read_b64_tr_b16 v[84:85], v115 offset:43008
	ds_read_b64_tr_b16 v[86:87], v116 offset:40960
	ds_read_b64_tr_b16 v[88:89], v116 offset:43008
	ds_read_b64_tr_b16 v[90:91], v117 offset:40960
	ds_read_b64_tr_b16 v[92:93], v117 offset:43008
	ds_read_b64_tr_b16 v[94:95], v119 offset:40960
	ds_read_b64_tr_b16 v[96:97], v119 offset:43008
	s_waitcnt lgkmcnt(6)
	s_setprio 1
	v_mfma_f32_16x16x32_bf16 v[46:49], v[82:85], v[74:77], v[46:49]
	v_mfma_f32_16x16x32_bf16 v[30:33], v[82:85], v[102:105], v[30:33]
	ds_read_b64_tr_b16 v[78:79], v115 offset:45056
	ds_read_b64_tr_b16 v[80:81], v115 offset:47104
	s_waitcnt lgkmcnt(6)
	v_mfma_f32_16x16x32_bf16 v[42:45], v[86:89], v[74:77], v[42:45]
	v_mfma_f32_16x16x32_bf16 v[26:29], v[86:89], v[102:105], v[26:29]
	ds_read_b64_tr_b16 v[66:67], v116 offset:45056
	ds_read_b64_tr_b16 v[68:69], v116 offset:47104
	s_waitcnt lgkmcnt(6)
	v_mfma_f32_16x16x32_bf16 v[38:41], v[90:93], v[74:77], v[38:41]
	v_mfma_f32_16x16x32_bf16 v[22:25], v[90:93], v[102:105], v[22:25]
	ds_read_b64_tr_b16 v[58:59], v117 offset:45056
	ds_read_b64_tr_b16 v[60:61], v117 offset:47104
	s_waitcnt lgkmcnt(6)
	v_mfma_f32_16x16x32_bf16 v[34:37], v[94:97], v[74:77], v[34:37]
	v_mfma_f32_16x16x32_bf16 v[18:21], v[94:97], v[102:105], v[18:21]
	ds_read_b64_tr_b16 v[50:51], v119 offset:45056
	ds_read_b64_tr_b16 v[52:53], v119 offset:47104
	s_waitcnt lgkmcnt(6)
	v_mfma_f32_16x16x32_bf16 v[46:49], v[78:81], v[62:65], v[46:49]
	v_mfma_f32_16x16x32_bf16 v[30:33], v[78:81], v[106:109], v[30:33]
	s_waitcnt lgkmcnt(4)
	v_mfma_f32_16x16x32_bf16 v[42:45], v[66:69], v[62:65], v[42:45]
	v_mfma_f32_16x16x32_bf16 v[26:29], v[66:69], v[106:109], v[26:29]
	s_waitcnt lgkmcnt(2)
	v_mfma_f32_16x16x32_bf16 v[38:41], v[58:61], v[62:65], v[38:41]
	v_mfma_f32_16x16x32_bf16 v[22:25], v[58:61], v[106:109], v[22:25]
	s_waitcnt lgkmcnt(0)
	v_mfma_f32_16x16x32_bf16 v[34:37], v[50:53], v[62:65], v[34:37]
	v_mfma_f32_16x16x32_bf16 v[18:21], v[50:53], v[106:109], v[18:21]
	s_setprio 0
	s_xor_b64 s[42:43], s[76:77], -1
	s_mov_b32 s44, 1
	s_mov_b64 s[76:77], 0
	s_and_b64 vcc, exec, s[42:43]
	s_cbranch_vccz .LBB0_255

.LBB0_287:
	s_or_b32 s16, s25, s19
	s_cmp_gt_i32 s16, s14
	s_cbranch_scc1 .LBB0_286
	s_lshl_b32 s16, s16, 14
	s_and_b32 s16, s16, 0xc000
	s_add_i32 s16, s16, 0
	s_waitcnt lgkmcnt(0)
	v_add_u32_e32 v50, s16, v215
	v_and_b32_e32 v51, 64, v147
	v_add_u32_e32 v232, v50, v213
	v_add_u32_e32 v82, 64, v51
	v_add_u32_e32 v159, v50, v214
	ds_read_b128 v[78:81], v232 offset:32768
	ds_read_b128 v[70:73], v232 offset:34816
	ds_read_b128 v[74:77], v159 offset:32768
	ds_read_b128 v[66:69], v159 offset:34816
	ds_read_b128 v[62:65], v232 offset:36864
	ds_read_b128 v[54:57], v232 offset:38912
	ds_read_b128 v[58:61], v159 offset:36864
	ds_read_b128 v[50:53], v159 offset:38912
	s_add_i32 s25, s25, s23
	s_lshl_b32 s25, s25, 6
	s_or_b32 s42, s25, 63
	s_cmp_le_i32 s42, s4
	s_cselect_b64 s[42:43], -1, 0
	s_sub_i32 s44, s18, s25
	v_xor_b32_e32 v0, 16, v147
	s_cmpk_lt_i32 s44, 0x200
	v_cmp_lt_i32_e32 vcc, v0, v82
	v_xor_b32_e32 v83, 32, v147
	s_cselect_b64 s[44:45], -1, 0
	v_cndmask_b32_e32 v0, v147, v0, vcc
	v_cmp_lt_i32_e32 vcc, v83, v82
	s_and_b64 s[42:43], s[42:43], s[44:45]
	v_lshlrev_b32_e32 v0, 2, v0
	v_cndmask_b32_e32 v82, v147, v83, vcc
	v_lshlrev_b32_e32 v149, 2, v82
	s_andn2_b64 vcc, exec, s[42:43]
	s_mov_b64 s[42:43], -1
	s_cbranch_vccz .Lnw_p1
	v_lshl_add_u32 v114, s25, 2, v145
	v_add_u32_e32 v115, 0xffc, v114
	ds_read2_b32 v[82:83], v115 offset1:1
	ds_read2_b32 v[84:85], v115 offset0:2 offset1:3
	ds_read2_b32 v[86:87], v115 offset0:16 offset1:17
	ds_read2_b32 v[88:89], v115 offset0:18 offset1:19
	s_waitcnt lgkmcnt(4)
	s_setprio 1
	v_mfma_f32_16x16x32_bf16 v[78:81], v[78:81], v[2:5], 0
	v_mfma_f32_16x16x32_bf16 v[70:73], v[70:73], v[2:5], 0
	v_mfma_f32_16x16x32_bf16 v[62:65], v[62:65], v[2:5], 0
	v_mfma_f32_16x16x32_bf16 v[54:57], v[54:57], v[2:5], 0
	ds_read2_b32 v[90:91], v115 offset0:32 offset1:33
	ds_read2_b32 v[92:93], v115 offset0:34 offset1:35
	ds_read2_b32 v[94:95], v115 offset0:48 offset1:49
	ds_read2_b32 v[96:97], v115 offset0:50 offset1:51
	v_mfma_f32_16x16x32_bf16 v[78:81], v[74:77], v[6:9], v[78:81]
	v_mfma_f32_16x16x32_bf16 v[70:73], v[66:69], v[6:9], v[70:73]
	v_mfma_f32_16x16x32_bf16 v[62:65], v[58:61], v[6:9], v[62:65]
	v_mfma_f32_16x16x32_bf16 v[54:57], v[50:53], v[6:9], v[54:57]
	s_setprio 0
	s_waitcnt lgkmcnt(0)
	ds_read_b128 v[98:101], v232 offset:32768
	ds_read_b128 v[74:77], v159 offset:32768
	ds_read_b128 v[102:105], v232 offset:34816
	ds_read_b128 v[66:69], v159 offset:34816
	ds_read_b128 v[106:109], v232 offset:36864
	ds_read_b128 v[58:61], v159 offset:36864
	ds_read_b128 v[110:113], v232 offset:38912
	ds_read_b128 v[50:53], v159 offset:38912
	v_pk_fma_f32 v[78:79], v[78:79], s[36:37], v[82:83] op_sel_hi:[1,0,1]
	v_pk_fma_f32 v[80:81], v[80:81], s[36:37], v[84:85] op_sel_hi:[1,0,1]
	v_pk_fma_f32 v[70:71], v[70:71], s[36:37], v[86:87] op_sel_hi:[1,0,1]
	v_pk_fma_f32 v[72:73], v[72:73], s[36:37], v[88:89] op_sel_hi:[1,0,1]
	v_pk_fma_f32 v[62:63], v[62:63], s[36:37], v[90:91] op_sel_hi:[1,0,1]
	v_pk_fma_f32 v[64:65], v[64:65], s[36:37], v[92:93] op_sel_hi:[1,0,1]
	v_pk_fma_f32 v[54:55], v[54:55], s[36:37], v[94:95] op_sel_hi:[1,0,1]
	v_pk_fma_f32 v[56:57], v[56:57], s[36:37], v[96:97] op_sel_hi:[1,0,1]
	v_or_b32_e32 v117, s25, v216
	v_sub_u32_e32 v115, v144, v117
	v_subrev_u32_e32 v117, 0, v115
	v_cmp_gt_u32_e64 s[48:49], s3, v117
	v_subrev_u32_e32 v117, 1, v115
	v_cmp_gt_u32_e64 s[50:51], s3, v117
	v_subrev_u32_e32 v117, 2, v115
	v_cmp_gt_u32_e64 s[52:53], s3, v117
	v_subrev_u32_e32 v117, 3, v115
	v_cmp_gt_u32_e64 s[54:55], s3, v117
	v_subrev_u32_e32 v117, 16, v115
	v_cmp_gt_u32_e64 s[56:57], s3, v117
	v_subrev_u32_e32 v117, 17, v115
	v_cmp_gt_u32_e64 s[58:59], s3, v117
	v_subrev_u32_e32 v117, 18, v115
	v_cmp_gt_u32_e64 s[60:61], s3, v117
	v_subrev_u32_e32 v117, 19, v115
	v_cmp_gt_u32_e64 s[62:63], s3, v117
	v_cndmask_b32_e64 v78, v148, v78, s[48:49]
	v_cndmask_b32_e64 v79, v148, v79, s[50:51]
	v_cndmask_b32_e64 v80, v148, v80, s[52:53]
	v_cndmask_b32_e64 v81, v148, v81, s[54:55]
	v_cndmask_b32_e64 v70, v148, v70, s[56:57]
	v_cndmask_b32_e64 v71, v148, v71, s[58:59]
	v_cndmask_b32_e64 v72, v148, v72, s[60:61]
	v_cndmask_b32_e64 v73, v148, v73, s[62:63]
	v_subrev_u32_e32 v117, 32, v115
	v_cmp_gt_u32_e64 s[48:49], s3, v117
	v_subrev_u32_e32 v117, 33, v115
	v_cmp_gt_u32_e64 s[50:51], s3, v117
	v_subrev_u32_e32 v117, 34, v115
	v_cmp_gt_u32_e64 s[52:53], s3, v117
	v_subrev_u32_e32 v117, 35, v115
	v_cmp_gt_u32_e64 s[54:55], s3, v117
	v_subrev_u32_e32 v117, 48, v115
	v_cmp_gt_u32_e64 s[56:57], s3, v117
	v_subrev_u32_e32 v117, 49, v115
	v_cmp_gt_u32_e64 s[58:59], s3, v117
	v_subrev_u32_e32 v117, 50, v115
	v_cmp_gt_u32_e64 s[60:61], s3, v117
	v_subrev_u32_e32 v117, 51, v115
	v_cmp_gt_u32_e64 s[62:63], s3, v117
	v_cndmask_b32_e64 v62, v148, v62, s[48:49]
	v_cndmask_b32_e64 v63, v148, v63, s[50:51]
	v_cndmask_b32_e64 v64, v148, v64, s[52:53]
	v_cndmask_b32_e64 v65, v148, v65, s[54:55]
	v_cndmask_b32_e64 v54, v148, v54, s[56:57]
	v_cndmask_b32_e64 v55, v148, v55, s[58:59]
	v_cndmask_b32_e64 v56, v148, v56, s[60:61]
	v_cndmask_b32_e64 v57, v148, v57, s[62:63]
	v_max3_f32 v116, v78, v79, v80
	v_max3_f32 v116, v116, v81, v70
	v_max3_f32 v116, v116, v71, v72
	v_max3_f32 v116, v116, v73, v62
	v_max3_f32 v116, v116, v63, v64
	v_max3_f32 v116, v116, v65, v54
	v_max3_f32 v116, v116, v55, v56
	v_max3_f32 v116, v116, v57, s29
	v_mov_b32_e32 v117, v116
	s_nop 1
	v_permlane16_swap_b32_e32 v116, v117
	v_max_f32_e32 v116, v116, v117
	v_mov_b32_e32 v117, v116
	s_nop 1
	v_permlane32_swap_b32_e32 v116, v117
	v_max_f32_e32 v116, v116, v117
	v_max_f32_e32 v121, v166, v116
	v_sub_f32_e32 v118, v166, v121
	v_cmp_lt_f32_e32 vcc, s30, v121
	v_exp_f32_e32 v118, v118
	v_mov_b32_e32 v166, v121
	v_cndmask_b32_e32 v120, 0, v121, vcc
	v_pk_mul_f32 v[46:47], v[46:47], v[118:119] op_sel_hi:[1,0]
	v_pk_mul_f32 v[48:49], v[48:49], v[118:119] op_sel_hi:[1,0]
	v_pk_mul_f32 v[42:43], v[42:43], v[118:119] op_sel_hi:[1,0]
	v_pk_mul_f32 v[44:45], v[44:45], v[118:119] op_sel_hi:[1,0]
	v_pk_mul_f32 v[38:39], v[38:39], v[118:119] op_sel_hi:[1,0]
	v_pk_mul_f32 v[40:41], v[40:41], v[118:119] op_sel_hi:[1,0]
	v_pk_mul_f32 v[34:35], v[34:35], v[118:119] op_sel_hi:[1,0]
	v_pk_mul_f32 v[36:37], v[36:37], v[118:119] op_sel_hi:[1,0]
	v_pk_add_f32 v[78:79], v[78:79], v[120:121] op_sel_hi:[1,0] neg_lo:[0,1] neg_hi:[0,1]
	v_pk_add_f32 v[80:81], v[80:81], v[120:121] op_sel_hi:[1,0] neg_lo:[0,1] neg_hi:[0,1]
	v_pk_add_f32 v[70:71], v[70:71], v[120:121] op_sel_hi:[1,0] neg_lo:[0,1] neg_hi:[0,1]
	v_pk_add_f32 v[72:73], v[72:73], v[120:121] op_sel_hi:[1,0] neg_lo:[0,1] neg_hi:[0,1]
	v_pk_add_f32 v[62:63], v[62:63], v[120:121] op_sel_hi:[1,0] neg_lo:[0,1] neg_hi:[0,1]
	v_pk_add_f32 v[64:65], v[64:65], v[120:121] op_sel_hi:[1,0] neg_lo:[0,1] neg_hi:[0,1]
	v_pk_add_f32 v[54:55], v[54:55], v[120:121] op_sel_hi:[1,0] neg_lo:[0,1] neg_hi:[0,1]
	v_pk_add_f32 v[56:57], v[56:57], v[120:121] op_sel_hi:[1,0] neg_lo:[0,1] neg_hi:[0,1]
	v_exp_f32_e32 v78, v78
	v_exp_f32_e32 v79, v79
	v_exp_f32_e32 v80, v80
	v_exp_f32_e32 v81, v81
	v_exp_f32_e32 v70, v70
	v_exp_f32_e32 v71, v71
	v_exp_f32_e32 v72, v72
	v_exp_f32_e32 v73, v73
	v_exp_f32_e32 v62, v62
	v_exp_f32_e32 v63, v63
	v_exp_f32_e32 v64, v64
	v_exp_f32_e32 v65, v65
	v_exp_f32_e32 v54, v54
	v_exp_f32_e32 v55, v55
	v_exp_f32_e32 v56, v56
	v_exp_f32_e32 v57, v57
	s_nop 0
	v_pk_add_f32 v[82:83], v[78:79], v[80:81]
	v_pk_add_f32 v[84:85], v[70:71], v[72:73]
	v_pk_add_f32 v[86:87], v[62:63], v[64:65]
	v_pk_add_f32 v[88:89], v[54:55], v[56:57]
	v_pk_add_f32 v[82:83], v[82:83], v[84:85]
	v_pk_add_f32 v[86:87], v[86:87], v[88:89]
	s_nop 0
	v_pk_add_f32 v[82:83], v[82:83], v[86:87]
	s_nop 0
	v_add_f32_e32 v82, v82, v83
	v_fma_f32 v160, v160, v118, v82
	v_cvt_pk_bf16_f32 v73, v72, v73
	v_cvt_pk_bf16_f32 v72, v70, v71
	v_cvt_pk_bf16_f32 v71, v80, v81
	v_cvt_pk_bf16_f32 v70, v78, v79
	v_cvt_pk_bf16_f32 v62, v62, v63
	v_cvt_pk_bf16_f32 v63, v64, v65
	v_cvt_pk_bf16_f32 v64, v54, v55
	v_cvt_pk_bf16_f32 v65, v56, v57
	v_add_u32_e32 v115, 0xfbc, v114
	s_waitcnt lgkmcnt(0)
	ds_read2_b32 v[82:83], v115 offset1:1
	ds_read2_b32 v[84:85], v115 offset0:2 offset1:3
	ds_read2_b32 v[86:87], v115 offset0:16 offset1:17
	ds_read2_b32 v[88:89], v115 offset0:18 offset1:19
	ds_read2_b32 v[90:91], v115 offset0:32 offset1:33
	ds_read2_b32 v[92:93], v115 offset0:34 offset1:35
	ds_read2_b32 v[94:95], v115 offset0:48 offset1:49
	ds_read2_b32 v[96:97], v115 offset0:50 offset1:51
	s_setprio 1
	v_mfma_f32_16x16x32_bf16 v[98:101], v[98:101], v[10:13], 0
	v_mfma_f32_16x16x32_bf16 v[102:105], v[102:105], v[10:13], 0
	v_mfma_f32_16x16x32_bf16 v[106:109], v[106:109], v[10:13], 0
	v_mfma_f32_16x16x32_bf16 v[110:113], v[110:113], v[10:13], 0
	v_mfma_f32_16x16x32_bf16 v[98:101], v[74:77], v[14:17], v[98:101]
	v_mfma_f32_16x16x32_bf16 v[102:105], v[66:69], v[14:17], v[102:105]
	v_mfma_f32_16x16x32_bf16 v[106:109], v[58:61], v[14:17], v[106:109]
	v_mfma_f32_16x16x32_bf16 v[110:113], v[50:53], v[14:17], v[110:113]
	s_setprio 0
	s_waitcnt lgkmcnt(0)
	s_nop 6
	v_pk_fma_f32 v[98:99], v[98:99], s[36:37], v[82:83] op_sel_hi:[1,0,1]
	v_pk_fma_f32 v[100:101], v[100:101], s[36:37], v[84:85] op_sel_hi:[1,0,1]
	v_pk_fma_f32 v[102:103], v[102:103], s[36:37], v[86:87] op_sel_hi:[1,0,1]
	v_pk_fma_f32 v[104:105], v[104:105], s[36:37], v[88:89] op_sel_hi:[1,0,1]
	v_pk_fma_f32 v[106:107], v[106:107], s[36:37], v[90:91] op_sel_hi:[1,0,1]
	v_pk_fma_f32 v[108:109], v[108:109], s[36:37], v[92:93] op_sel_hi:[1,0,1]
	v_pk_fma_f32 v[110:111], v[110:111], s[36:37], v[94:95] op_sel_hi:[1,0,1]
	v_pk_fma_f32 v[112:113], v[112:113], s[36:37], v[96:97] op_sel_hi:[1,0,1]
	v_or_b32_e32 v117, s25, v216
	v_sub_u32_e32 v115, v144, v117
	v_add_u32_e32 v115, 16, v115
	v_subrev_u32_e32 v117, 0, v115
	v_cmp_gt_u32_e64 s[48:49], s3, v117
	v_subrev_u32_e32 v117, 1, v115
	v_cmp_gt_u32_e64 s[50:51], s3, v117
	v_subrev_u32_e32 v117, 2, v115
	v_cmp_gt_u32_e64 s[52:53], s3, v117
	v_subrev_u32_e32 v117, 3, v115
	v_cmp_gt_u32_e64 s[54:55], s3, v117
	v_subrev_u32_e32 v117, 16, v115
	v_cmp_gt_u32_e64 s[56:57], s3, v117
	v_subrev_u32_e32 v117, 17, v115
	v_cmp_gt_u32_e64 s[58:59], s3, v117
	v_subrev_u32_e32 v117, 18, v115
	v_cmp_gt_u32_e64 s[60:61], s3, v117
	v_subrev_u32_e32 v117, 19, v115
	v_cmp_gt_u32_e64 s[62:63], s3, v117
	v_cndmask_b32_e64 v98, v148, v98, s[48:49]
	v_cndmask_b32_e64 v99, v148, v99, s[50:51]
	v_cndmask_b32_e64 v100, v148, v100, s[52:53]
	v_cndmask_b32_e64 v101, v148, v101, s[54:55]
	v_cndmask_b32_e64 v102, v148, v102, s[56:57]
	v_cndmask_b32_e64 v103, v148, v103, s[58:59]
	v_cndmask_b32_e64 v104, v148, v104, s[60:61]
	v_cndmask_b32_e64 v105, v148, v105, s[62:63]
	v_subrev_u32_e32 v117, 32, v115
	v_cmp_gt_u32_e64 s[48:49], s3, v117
	v_subrev_u32_e32 v117, 33, v115
	v_cmp_gt_u32_e64 s[50:51], s3, v117
	v_subrev_u32_e32 v117, 34, v115
	v_cmp_gt_u32_e64 s[52:53], s3, v117
	v_subrev_u32_e32 v117, 35, v115
	v_cmp_gt_u32_e64 s[54:55], s3, v117
	v_subrev_u32_e32 v117, 48, v115
	v_cmp_gt_u32_e64 s[56:57], s3, v117
	v_subrev_u32_e32 v117, 49, v115
	v_cmp_gt_u32_e64 s[58:59], s3, v117
	v_subrev_u32_e32 v117, 50, v115
	v_cmp_gt_u32_e64 s[60:61], s3, v117
	v_subrev_u32_e32 v117, 51, v115
	v_cmp_gt_u32_e64 s[62:63], s3, v117
	v_cndmask_b32_e64 v106, v148, v106, s[48:49]
	v_cndmask_b32_e64 v107, v148, v107, s[50:51]
	v_cndmask_b32_e64 v108, v148, v108, s[52:53]
	v_cndmask_b32_e64 v109, v148, v109, s[54:55]
	v_cndmask_b32_e64 v110, v148, v110, s[56:57]
	v_cndmask_b32_e64 v111, v148, v111, s[58:59]
	v_cndmask_b32_e64 v112, v148, v112, s[60:61]
	v_cndmask_b32_e64 v113, v148, v113, s[62:63]
	v_max3_f32 v116, v98, v99, v100
	v_max3_f32 v116, v116, v101, v102
	v_max3_f32 v116, v116, v103, v104
	v_max3_f32 v116, v116, v105, v106
	v_max3_f32 v116, v116, v107, v108
	v_max3_f32 v116, v116, v109, v110
	v_max3_f32 v116, v116, v111, v112
	v_max3_f32 v116, v116, v113, s29
	v_mov_b32_e32 v117, v116
	s_nop 1
	v_permlane16_swap_b32_e32 v116, v117
	v_max_f32_e32 v116, v116, v117
	v_mov_b32_e32 v117, v116
	s_nop 1
	v_permlane32_swap_b32_e32 v116, v117
	v_max_f32_e32 v116, v116, v117
	v_max_f32_e32 v121, v167, v116
	v_sub_f32_e32 v118, v167, v121
	v_cmp_lt_f32_e32 vcc, s30, v121
	v_exp_f32_e32 v118, v118
	v_mov_b32_e32 v167, v121
	v_cndmask_b32_e32 v120, 0, v121, vcc
	v_pk_mul_f32 v[30:31], v[30:31], v[118:119] op_sel_hi:[1,0]
	v_pk_mul_f32 v[32:33], v[32:33], v[118:119] op_sel_hi:[1,0]
	v_pk_mul_f32 v[26:27], v[26:27], v[118:119] op_sel_hi:[1,0]
	v_pk_mul_f32 v[28:29], v[28:29], v[118:119] op_sel_hi:[1,0]
	v_pk_mul_f32 v[22:23], v[22:23], v[118:119] op_sel_hi:[1,0]
	v_pk_mul_f32 v[24:25], v[24:25], v[118:119] op_sel_hi:[1,0]
	v_pk_mul_f32 v[18:19], v[18:19], v[118:119] op_sel_hi:[1,0]
	v_pk_mul_f32 v[20:21], v[20:21], v[118:119] op_sel_hi:[1,0]
	v_pk_add_f32 v[98:99], v[98:99], v[120:121] op_sel_hi:[1,0] neg_lo:[0,1] neg_hi:[0,1]
	v_pk_add_f32 v[100:101], v[100:101], v[120:121] op_sel_hi:[1,0] neg_lo:[0,1] neg_hi:[0,1]
	v_pk_add_f32 v[102:103], v[102:103], v[120:121] op_sel_hi:[1,0] neg_lo:[0,1] neg_hi:[0,1]
	v_pk_add_f32 v[104:105], v[104:105], v[120:121] op_sel_hi:[1,0] neg_lo:[0,1] neg_hi:[0,1]
	v_pk_add_f32 v[106:107], v[106:107], v[120:121] op_sel_hi:[1,0] neg_lo:[0,1] neg_hi:[0,1]
	v_pk_add_f32 v[108:109], v[108:109], v[120:121] op_sel_hi:[1,0] neg_lo:[0,1] neg_hi:[0,1]
	v_pk_add_f32 v[110:111], v[110:111], v[120:121] op_sel_hi:[1,0] neg_lo:[0,1] neg_hi:[0,1]
	v_pk_add_f32 v[112:113], v[112:113], v[120:121] op_sel_hi:[1,0] neg_lo:[0,1] neg_hi:[0,1]
	v_exp_f32_e32 v98, v98
	v_exp_f32_e32 v99, v99
	v_exp_f32_e32 v100, v100
	v_exp_f32_e32 v101, v101
	v_exp_f32_e32 v102, v102
	v_exp_f32_e32 v103, v103
	v_exp_f32_e32 v104, v104
	v_exp_f32_e32 v105, v105
	v_exp_f32_e32 v106, v106
	v_exp_f32_e32 v107, v107
	v_exp_f32_e32 v108, v108
	v_exp_f32_e32 v109, v109
	v_exp_f32_e32 v110, v110
	v_exp_f32_e32 v111, v111
	v_exp_f32_e32 v112, v112
	v_exp_f32_e32 v113, v113
	s_nop 0
	v_pk_add_f32 v[82:83], v[98:99], v[100:101]
	v_pk_add_f32 v[84:85], v[102:103], v[104:105]
	v_pk_add_f32 v[86:87], v[106:107], v[108:109]
	v_pk_add_f32 v[88:89], v[110:111], v[112:113]
	v_pk_add_f32 v[82:83], v[82:83], v[84:85]
	v_pk_add_f32 v[86:87], v[86:87], v[88:89]
	s_nop 0
	v_pk_add_f32 v[82:83], v[82:83], v[86:87]
	s_nop 0
	v_add_f32_e32 v82, v82, v83
	v_fma_f32 v161, v161, v118, v82
	v_cvt_pk_bf16_f32 v105, v104, v105
	v_cvt_pk_bf16_f32 v104, v102, v103
	v_cvt_pk_bf16_f32 v103, v100, v101
	v_cvt_pk_bf16_f32 v102, v98, v99
	v_cvt_pk_bf16_f32 v106, v106, v107
	v_cvt_pk_bf16_f32 v107, v108, v109
	v_cvt_pk_bf16_f32 v108, v110, v111
	v_cvt_pk_bf16_f32 v109, v112, v113
	s_branch .Lnw_pv
.Lnw_p1:
	v_lshl_add_u32 v114, s25, 2, v145
	v_add_u32_e32 v115, 0xffc, v114
	ds_read2_b32 v[82:83], v115 offset1:1
	ds_read2_b32 v[84:85], v115 offset0:2 offset1:3
	ds_read2_b32 v[86:87], v115 offset0:16 offset1:17
	ds_read2_b32 v[88:89], v115 offset0:18 offset1:19
	s_waitcnt lgkmcnt(4)
	s_setprio 1
	v_mfma_f32_16x16x32_bf16 v[78:81], v[78:81], v[2:5], 0
	v_mfma_f32_16x16x32_bf16 v[70:73], v[70:73], v[2:5], 0
	v_mfma_f32_16x16x32_bf16 v[62:65], v[62:65], v[2:5], 0
	v_mfma_f32_16x16x32_bf16 v[54:57], v[54:57], v[2:5], 0
	ds_read2_b32 v[90:91], v115 offset0:32 offset1:33
	ds_read2_b32 v[92:93], v115 offset0:34 offset1:35
	ds_read2_b32 v[94:95], v115 offset0:48 offset1:49
	ds_read2_b32 v[96:97], v115 offset0:50 offset1:51
	v_mfma_f32_16x16x32_bf16 v[78:81], v[74:77], v[6:9], v[78:81]
	v_mfma_f32_16x16x32_bf16 v[70:73], v[66:69], v[6:9], v[70:73]
	v_mfma_f32_16x16x32_bf16 v[62:65], v[58:61], v[6:9], v[62:65]
	v_mfma_f32_16x16x32_bf16 v[54:57], v[50:53], v[6:9], v[54:57]
	s_setprio 0
	s_waitcnt lgkmcnt(0)
	ds_read_b128 v[98:101], v232 offset:32768
	ds_read_b128 v[74:77], v159 offset:32768
	ds_read_b128 v[102:105], v232 offset:34816
	ds_read_b128 v[66:69], v159 offset:34816
	ds_read_b128 v[106:109], v232 offset:36864
	ds_read_b128 v[58:61], v159 offset:36864
	ds_read_b128 v[110:113], v232 offset:38912
	ds_read_b128 v[50:53], v159 offset:38912
	v_pk_fma_f32 v[78:79], v[78:79], s[36:37], v[82:83] op_sel_hi:[1,0,1]
	v_pk_fma_f32 v[80:81], v[80:81], s[36:37], v[84:85] op_sel_hi:[1,0,1]
	v_pk_fma_f32 v[70:71], v[70:71], s[36:37], v[86:87] op_sel_hi:[1,0,1]
	v_pk_fma_f32 v[72:73], v[72:73], s[36:37], v[88:89] op_sel_hi:[1,0,1]
	v_pk_fma_f32 v[62:63], v[62:63], s[36:37], v[90:91] op_sel_hi:[1,0,1]
	v_pk_fma_f32 v[64:65], v[64:65], s[36:37], v[92:93] op_sel_hi:[1,0,1]
	v_pk_fma_f32 v[54:55], v[54:55], s[36:37], v[94:95] op_sel_hi:[1,0,1]
	v_pk_fma_f32 v[56:57], v[56:57], s[36:37], v[96:97] op_sel_hi:[1,0,1]
	v_max3_f32 v116, v78, v79, v80
	v_max3_f32 v116, v116, v81, v70
	v_max3_f32 v116, v116, v71, v72
	v_max3_f32 v116, v116, v73, v62
	v_max3_f32 v116, v116, v63, v64
	v_max3_f32 v116, v116, v65, v54
	v_max3_f32 v116, v116, v55, v56
	v_max3_f32 v116, v116, v57, s29
	v_mov_b32_e32 v117, v116
	s_nop 1
	v_permlane16_swap_b32_e32 v116, v117
	v_max_f32_e32 v116, v116, v117
	v_mov_b32_e32 v117, v116
	s_nop 1
	v_permlane32_swap_b32_e32 v116, v117
	v_max_f32_e32 v116, v116, v117
	v_max_f32_e32 v121, v166, v116
	v_sub_f32_e32 v118, v166, v121
	v_exp_f32_e32 v118, v118
	v_mov_b32_e32 v166, v121
	v_mov_b32_e32 v120, v121
	v_pk_mul_f32 v[46:47], v[46:47], v[118:119] op_sel_hi:[1,0]
	v_pk_mul_f32 v[48:49], v[48:49], v[118:119] op_sel_hi:[1,0]
	v_pk_mul_f32 v[42:43], v[42:43], v[118:119] op_sel_hi:[1,0]
	v_pk_mul_f32 v[44:45], v[44:45], v[118:119] op_sel_hi:[1,0]
	v_pk_mul_f32 v[38:39], v[38:39], v[118:119] op_sel_hi:[1,0]
	v_pk_mul_f32 v[40:41], v[40:41], v[118:119] op_sel_hi:[1,0]
	v_pk_mul_f32 v[34:35], v[34:35], v[118:119] op_sel_hi:[1,0]
	v_pk_mul_f32 v[36:37], v[36:37], v[118:119] op_sel_hi:[1,0]
	v_pk_add_f32 v[78:79], v[78:79], v[120:121] op_sel_hi:[1,0] neg_lo:[0,1] neg_hi:[0,1]
	v_pk_add_f32 v[80:81], v[80:81], v[120:121] op_sel_hi:[1,0] neg_lo:[0,1] neg_hi:[0,1]
	v_pk_add_f32 v[70:71], v[70:71], v[120:121] op_sel_hi:[1,0] neg_lo:[0,1] neg_hi:[0,1]
	v_pk_add_f32 v[72:73], v[72:73], v[120:121] op_sel_hi:[1,0] neg_lo:[0,1] neg_hi:[0,1]
	v_pk_add_f32 v[62:63], v[62:63], v[120:121] op_sel_hi:[1,0] neg_lo:[0,1] neg_hi:[0,1]
	v_pk_add_f32 v[64:65], v[64:65], v[120:121] op_sel_hi:[1,0] neg_lo:[0,1] neg_hi:[0,1]
	v_pk_add_f32 v[54:55], v[54:55], v[120:121] op_sel_hi:[1,0] neg_lo:[0,1] neg_hi:[0,1]
	v_pk_add_f32 v[56:57], v[56:57], v[120:121] op_sel_hi:[1,0] neg_lo:[0,1] neg_hi:[0,1]
	v_exp_f32_e32 v78, v78
	v_exp_f32_e32 v79, v79
	v_exp_f32_e32 v80, v80
	v_exp_f32_e32 v81, v81
	v_exp_f32_e32 v70, v70
	v_exp_f32_e32 v71, v71
	v_exp_f32_e32 v72, v72
	v_exp_f32_e32 v73, v73
	v_exp_f32_e32 v62, v62
	v_exp_f32_e32 v63, v63
	v_exp_f32_e32 v64, v64
	v_exp_f32_e32 v65, v65
	v_exp_f32_e32 v54, v54
	v_exp_f32_e32 v55, v55
	v_exp_f32_e32 v56, v56
	v_exp_f32_e32 v57, v57
	s_nop 0
	v_pk_add_f32 v[82:83], v[78:79], v[80:81]
	v_pk_add_f32 v[84:85], v[70:71], v[72:73]
	v_pk_add_f32 v[86:87], v[62:63], v[64:65]
	v_pk_add_f32 v[88:89], v[54:55], v[56:57]
	v_pk_add_f32 v[82:83], v[82:83], v[84:85]
	v_pk_add_f32 v[86:87], v[86:87], v[88:89]
	s_nop 0
	v_pk_add_f32 v[82:83], v[82:83], v[86:87]
	s_nop 0
	v_add_f32_e32 v82, v82, v83
	v_fma_f32 v160, v160, v118, v82
	v_cvt_pk_bf16_f32 v73, v72, v73
	v_cvt_pk_bf16_f32 v72, v70, v71
	v_cvt_pk_bf16_f32 v71, v80, v81
	v_cvt_pk_bf16_f32 v70, v78, v79
	v_cvt_pk_bf16_f32 v62, v62, v63
	v_cvt_pk_bf16_f32 v63, v64, v65
	v_cvt_pk_bf16_f32 v64, v54, v55
	v_cvt_pk_bf16_f32 v65, v56, v57
	v_add_u32_e32 v115, 0xfbc, v114
	s_waitcnt lgkmcnt(0)
	ds_read2_b32 v[82:83], v115 offset1:1
	ds_read2_b32 v[84:85], v115 offset0:2 offset1:3
	ds_read2_b32 v[86:87], v115 offset0:16 offset1:17
	ds_read2_b32 v[88:89], v115 offset0:18 offset1:19
	ds_read2_b32 v[90:91], v115 offset0:32 offset1:33
	ds_read2_b32 v[92:93], v115 offset0:34 offset1:35
	ds_read2_b32 v[94:95], v115 offset0:48 offset1:49
	ds_read2_b32 v[96:97], v115 offset0:50 offset1:51
	s_setprio 1
	v_mfma_f32_16x16x32_bf16 v[98:101], v[98:101], v[10:13], 0
	v_mfma_f32_16x16x32_bf16 v[102:105], v[102:105], v[10:13], 0
	v_mfma_f32_16x16x32_bf16 v[106:109], v[106:109], v[10:13], 0
	v_mfma_f32_16x16x32_bf16 v[110:113], v[110:113], v[10:13], 0
	v_mfma_f32_16x16x32_bf16 v[98:101], v[74:77], v[14:17], v[98:101]
	v_mfma_f32_16x16x32_bf16 v[102:105], v[66:69], v[14:17], v[102:105]
	v_mfma_f32_16x16x32_bf16 v[106:109], v[58:61], v[14:17], v[106:109]
	v_mfma_f32_16x16x32_bf16 v[110:113], v[50:53], v[14:17], v[110:113]
	s_setprio 0
	s_waitcnt lgkmcnt(0)
	s_nop 6
	v_pk_fma_f32 v[98:99], v[98:99], s[36:37], v[82:83] op_sel_hi:[1,0,1]
	v_pk_fma_f32 v[100:101], v[100:101], s[36:37], v[84:85] op_sel_hi:[1,0,1]
	v_pk_fma_f32 v[102:103], v[102:103], s[36:37], v[86:87] op_sel_hi:[1,0,1]
	v_pk_fma_f32 v[104:105], v[104:105], s[36:37], v[88:89] op_sel_hi:[1,0,1]
	v_pk_fma_f32 v[106:107], v[106:107], s[36:37], v[90:91] op_sel_hi:[1,0,1]
	v_pk_fma_f32 v[108:109], v[108:109], s[36:37], v[92:93] op_sel_hi:[1,0,1]
	v_pk_fma_f32 v[110:111], v[110:111], s[36:37], v[94:95] op_sel_hi:[1,0,1]
	v_pk_fma_f32 v[112:113], v[112:113], s[36:37], v[96:97] op_sel_hi:[1,0,1]
	v_max3_f32 v116, v98, v99, v100
	v_max3_f32 v116, v116, v101, v102
	v_max3_f32 v116, v116, v103, v104
	v_max3_f32 v116, v116, v105, v106
	v_max3_f32 v116, v116, v107, v108
	v_max3_f32 v116, v116, v109, v110
	v_max3_f32 v116, v116, v111, v112
	v_max3_f32 v116, v116, v113, s29
	v_mov_b32_e32 v117, v116
	s_nop 1
	v_permlane16_swap_b32_e32 v116, v117
	v_max_f32_e32 v116, v116, v117
	v_mov_b32_e32 v117, v116
	s_nop 1
	v_permlane32_swap_b32_e32 v116, v117
	v_max_f32_e32 v116, v116, v117
	v_max_f32_e32 v121, v167, v116
	v_sub_f32_e32 v118, v167, v121
	v_exp_f32_e32 v118, v118
	v_mov_b32_e32 v167, v121
	v_mov_b32_e32 v120, v121
	v_pk_mul_f32 v[30:31], v[30:31], v[118:119] op_sel_hi:[1,0]
	v_pk_mul_f32 v[32:33], v[32:33], v[118:119] op_sel_hi:[1,0]
	v_pk_mul_f32 v[26:27], v[26:27], v[118:119] op_sel_hi:[1,0]
	v_pk_mul_f32 v[28:29], v[28:29], v[118:119] op_sel_hi:[1,0]
	v_pk_mul_f32 v[22:23], v[22:23], v[118:119] op_sel_hi:[1,0]
	v_pk_mul_f32 v[24:25], v[24:25], v[118:119] op_sel_hi:[1,0]
	v_pk_mul_f32 v[18:19], v[18:19], v[118:119] op_sel_hi:[1,0]
	v_pk_mul_f32 v[20:21], v[20:21], v[118:119] op_sel_hi:[1,0]
	v_pk_add_f32 v[98:99], v[98:99], v[120:121] op_sel_hi:[1,0] neg_lo:[0,1] neg_hi:[0,1]
	v_pk_add_f32 v[100:101], v[100:101], v[120:121] op_sel_hi:[1,0] neg_lo:[0,1] neg_hi:[0,1]
	v_pk_add_f32 v[102:103], v[102:103], v[120:121] op_sel_hi:[1,0] neg_lo:[0,1] neg_hi:[0,1]
	v_pk_add_f32 v[104:105], v[104:105], v[120:121] op_sel_hi:[1,0] neg_lo:[0,1] neg_hi:[0,1]
	v_pk_add_f32 v[106:107], v[106:107], v[120:121] op_sel_hi:[1,0] neg_lo:[0,1] neg_hi:[0,1]
	v_pk_add_f32 v[108:109], v[108:109], v[120:121] op_sel_hi:[1,0] neg_lo:[0,1] neg_hi:[0,1]
	v_pk_add_f32 v[110:111], v[110:111], v[120:121] op_sel_hi:[1,0] neg_lo:[0,1] neg_hi:[0,1]
	v_pk_add_f32 v[112:113], v[112:113], v[120:121] op_sel_hi:[1,0] neg_lo:[0,1] neg_hi:[0,1]
	v_exp_f32_e32 v98, v98
	v_exp_f32_e32 v99, v99
	v_exp_f32_e32 v100, v100
	v_exp_f32_e32 v101, v101
	v_exp_f32_e32 v102, v102
	v_exp_f32_e32 v103, v103
	v_exp_f32_e32 v104, v104
	v_exp_f32_e32 v105, v105
	v_exp_f32_e32 v106, v106
	v_exp_f32_e32 v107, v107
	v_exp_f32_e32 v108, v108
	v_exp_f32_e32 v109, v109
	v_exp_f32_e32 v110, v110
	v_exp_f32_e32 v111, v111
	v_exp_f32_e32 v112, v112
	v_exp_f32_e32 v113, v113
	s_nop 0
	v_pk_add_f32 v[82:83], v[98:99], v[100:101]
	v_pk_add_f32 v[84:85], v[102:103], v[104:105]
	v_pk_add_f32 v[86:87], v[106:107], v[108:109]
	v_pk_add_f32 v[88:89], v[110:111], v[112:113]
	v_pk_add_f32 v[82:83], v[82:83], v[84:85]
	v_pk_add_f32 v[86:87], v[86:87], v[88:89]
	s_nop 0
	v_pk_add_f32 v[82:83], v[82:83], v[86:87]
	s_nop 0
	v_add_f32_e32 v82, v82, v83
	v_fma_f32 v161, v161, v118, v82
	v_cvt_pk_bf16_f32 v105, v104, v105
	v_cvt_pk_bf16_f32 v104, v102, v103
	v_cvt_pk_bf16_f32 v103, v100, v101
	v_cvt_pk_bf16_f32 v102, v98, v99
	v_cvt_pk_bf16_f32 v106, v106, v107
	v_cvt_pk_bf16_f32 v107, v108, v109
	v_cvt_pk_bf16_f32 v108, v110, v111
	v_cvt_pk_bf16_f32 v109, v112, v113
.Lnw_pv:
	v_add3_u32 v114, s16, v217, v219
	v_add_u32_e32 v115, v114, v220
	v_add_u32_e32 v116, v114, v221
	v_add_u32_e32 v117, v114, v222
	v_add_u32_e32 v119, v114, v223
	ds_read_b64_tr_b16 v[82:83], v115 offset:40960
	ds_read_b64_tr_b16 v[84:85], v115 offset:43008
	ds_read_b64_tr_b16 v[86:87], v116 offset:40960
	ds_read_b64_tr_b16 v[88:89], v116 offset:43008
	ds_read_b64_tr_b16 v[90:91], v117 offset:40960
	ds_read_b64_tr_b16 v[92:93], v117 offset:43008
	ds_read_b64_tr_b16 v[94:95], v119 offset:40960
	ds_read_b64_tr_b16 v[96:97], v119 offset:43008
	s_waitcnt lgkmcnt(6)
	s_setprio 1
	v_mfma_f32_16x16x32_bf16 v[46:49], v[82:85], v[70:73], v[46:49]
	v_mfma_f32_16x16x32_bf16 v[30:33], v[82:85], v[102:105], v[30:33]
	ds_read_b64_tr_b16 v[74:75], v115 offset:45056
	ds_read_b64_tr_b16 v[76:77], v115 offset:47104
	s_waitcnt lgkmcnt(6)
	v_mfma_f32_16x16x32_bf16 v[42:45], v[86:89], v[70:73], v[42:45]
	v_mfma_f32_16x16x32_bf16 v[26:29], v[86:89], v[102:105], v[26:29]
	ds_read_b64_tr_b16 v[66:67], v116 offset:45056
	ds_read_b64_tr_b16 v[68:69], v116 offset:47104
	s_waitcnt lgkmcnt(6)
	v_mfma_f32_16x16x32_bf16 v[38:41], v[90:93], v[70:73], v[38:41]
	v_mfma_f32_16x16x32_bf16 v[22:25], v[90:93], v[102:105], v[22:25]
	ds_read_b64_tr_b16 v[58:59], v117 offset:45056
	ds_read_b64_tr_b16 v[60:61], v117 offset:47104
	s_waitcnt lgkmcnt(6)
	v_mfma_f32_16x16x32_bf16 v[34:37], v[94:97], v[70:73], v[34:37]
	v_mfma_f32_16x16x32_bf16 v[18:21], v[94:97], v[102:105], v[18:21]
	ds_read_b64_tr_b16 v[50:51], v119 offset:45056
	ds_read_b64_tr_b16 v[52:53], v119 offset:47104
	s_waitcnt lgkmcnt(6)
	v_mfma_f32_16x16x32_bf16 v[46:49], v[74:77], v[62:65], v[46:49]
	v_mfma_f32_16x16x32_bf16 v[30:33], v[74:77], v[106:109], v[30:33]
	s_waitcnt lgkmcnt(4)
	v_mfma_f32_16x16x32_bf16 v[42:45], v[66:69], v[62:65], v[42:45]
	v_mfma_f32_16x16x32_bf16 v[26:29], v[66:69], v[106:109], v[26:29]
	s_waitcnt lgkmcnt(2)
	v_mfma_f32_16x16x32_bf16 v[38:41], v[58:61], v[62:65], v[38:41]
	v_mfma_f32_16x16x32_bf16 v[22:25], v[58:61], v[106:109], v[22:25]
	s_waitcnt lgkmcnt(0)
	v_mfma_f32_16x16x32_bf16 v[34:37], v[50:53], v[62:65], v[34:37]
	v_mfma_f32_16x16x32_bf16 v[18:21], v[50:53], v[106:109], v[18:21]
	s_setprio 0
	s_xor_b64 s[42:43], s[72:73], -1
	s_mov_b32 s25, 1
	s_mov_b64 s[72:73], 0
	s_and_b64 vcc, exec, s[42:43]
	s_cbranch_vccz .LBB0_287
